# speedup vs baseline: 1.0042x; 1.0042x over previous
; #define STAGE(P, BASE, br, kt) do { const u16* _gb = (BASE) + ((size_t)(br) * K + (size_t)(kt) * BK); \
;     __builtin_amdgcn_global_load_lds((const unsigned*)(_gb + goff0), (unsigned*)((char*)(P) + tid * 16), 16, 0, 0); \
;     __builtin_amdgcn_global_load_lds((const unsigned*)(_gb + (size_t)64 * K + goff0), (unsigned*)((char*)(P) + tid * 16 + 8192), 16, 0, 0); } while (0)
; #define LDA(dst, b, h) _Pragma("unroll") for (int m = 0; m < 4; ++m) _Pragma("unroll") for (int k = 0; k < 2; ++k) \
;     dst[m][k] = *reinterpret_cast<const bf16x8*>((char*)SA(b, h) + lds_byte(wr * 64 + m * 16 + fr, k * 32 + fq * 8))
; #define LDB(dst, b, h) _Pragma("unroll") for (int n = 0; n < 2; ++n) _Pragma("unroll") for (int k = 0; k < 2; ++k) \
;     dst[n][k] = *reinterpret_cast<const bf16x8*>((char*)SB(b, h) + lds_byte(wc * 32 + n * 16 + fr, k * 32 + fq * 8))
; #define WAIT_V(n) asm volatile("s_waitcnt vmcnt(" #n ")" ::: "memory")
; #define WAIT_L(n) asm volatile("s_waitcnt lgkmcnt(" #n ")" ::: "memory")
; #define BAR __builtin_amdgcn_s_barrier()
; #define SCHED __builtin_amdgcn_sched_barrier(0)
; __device__ __forceinline__ void gemm_phase(KP p, char* shmc, const u16* __restrict__ A,
;                                            const u16* __restrict__ Bt, const int N, const int K, const int mode,
;                                            const float* __restrict__ xin, const float resw) {
;     ...
;     f32x4 acc[2][2][4][2];
; #pragma unroll
;     for (int a = 0; a < 2; ++a)
; #pragma unroll
;       for (int b = 0; b < 2; ++b)
; #pragma unroll
;         for (int m = 0; m < 4; ++m)
; #pragma unroll
;           for (int n = 0; n < 2; ++n) acc[a][b][m][n] = f32x4{0.f, 0.f, 0.f, 0.f};
;     bf16x8 At[4][2], B0[2][2], B1[2][2];
;     WAIT_V(0);
;     if (wr == 1) BAR;
;     BAR;
;     for (int t = 0; t < nt - 2; t += 2) {
;       LDB(B0, 0, 0); SCHED; LDA(At, 0, 0); STAGE(SA(1, 1), A, brow + HALF, t + 1);
;       WAIT_L(8); BAR; WAIT_L(0); MMA(0, 0, At, B0); BAR; SCHED;
;       LDB(B1, 0, 1); STAGE(SB(0, 0), Bt, bcol, t + 2);
;       BAR; WAIT_L(0); MMA(0, 1, At, B1); BAR;
;       LDA(At, 0, 1); STAGE(SA(0, 0), A, brow, t + 2);
;       BAR; WAIT_L(0); MMA(1, 0, At, B0); BAR; SCHED;
;       STAGE(SB(0, 1), Bt, bcol + HALF, t + 2);
;       WAIT_V(6); BAR; MMA(1, 1, At, B1); BAR;
.Lmy_noextra:
	s_add_u32 s8, s8, 0x80
	s_addc_u32 s9, s9, 0
	s_add_u32 s36, s36, 0x100
	s_addc_u32 s37, s37, 0
	s_add_u32 s26, s26, 0x100
	s_addc_u32 s27, s27, 0
	s_add_u32 s38, s38, 0x100
	s_addc_u32 s39, s39, 0
	s_waitcnt vmcnt(0)
	s_barrier
	ds_read_b128 v[194:197], v235 offset:0
	ds_read_b128 v[198:201], v235 offset:1024
	ds_read_b128 v[202:205], v235 offset:2048
	ds_read_b128 v[206:209], v235 offset:3072
	ds_read_b128 v[128:131], v234 offset:0
	ds_read_b128 v[132:135], v234 offset:1024
	ds_read_b128 v[136:139], v234 offset:2048
	ds_read_b128 v[140:143], v234 offset:3072
	ds_read_b128 v[144:147], v234 offset:4096
	ds_read_b128 v[148:151], v234 offset:5120
	ds_read_b128 v[152:155], v234 offset:6144
	ds_read_b128 v[156:159], v234 offset:7168
	s_waitcnt lgkmcnt(0)
	s_barrier
	s_add_u32 m0, s40, 0x0
	s_nop 0
	global_load_lds_dwordx4 v236, s[36:37]
	s_add_u32 m0, s40, 0x2000
	s_nop 0
	global_load_lds_dwordx4 v237, s[36:37]
	s_add_u32 s36, s36, 0x80
	s_addc_u32 s37, s37, 0
	s_cmp_lg_u32 s49, 2
	s_cbranch_scc1 .Lmy_entry_n
	s_sub_i32 s42, s73, 8
	s_cmp_lt_u32 s42, 4
	s_cbranch_scc1 .Lmy_entry_sw
.Lmy_entry_n:
	s_waitcnt vmcnt(12) lgkmcnt(0)
	s_barrier
	v_mfma_f32_16x16x32_bf16 v[120:123], v[194:197], v[128:131], 0
	v_mfma_f32_16x16x32_bf16 v[112:115], v[202:205], v[128:131], 0
	ds_read_b128 v[218:221], v235 offset:16384
	v_mfma_f32_16x16x32_bf16 v[104:107], v[194:197], v[136:139], 0
	ds_read_b128 v[222:225], v235 offset:17408
	v_mfma_f32_16x16x32_bf16 v[96:99], v[202:205], v[136:139], 0
	ds_read_b128 v[226:229], v235 offset:18432
	s_add_u32 m0, s40, 0x10000
	v_mfma_f32_16x16x32_bf16 v[88:91], v[194:197], v[144:147], 0
	ds_read_b128 v[230:233], v235 offset:19456
	v_mfma_f32_16x16x32_bf16 v[80:83], v[202:205], v[144:147], 0
	global_load_lds_dwordx4 v236, s[26:27]
	v_mfma_f32_16x16x32_bf16 v[72:75], v[194:197], v[152:155], 0
	v_mfma_f32_16x16x32_bf16 v[64:67], v[202:205], v[152:155], 0
	s_add_u32 m0, s40, 0x12000
	v_mfma_f32_16x16x32_bf16 v[120:123], v[198:201], v[132:135], v[120:123]
	v_mfma_f32_16x16x32_bf16 v[112:115], v[206:209], v[132:135], v[112:115]
	global_load_lds_dwordx4 v237, s[26:27]
	v_mfma_f32_16x16x32_bf16 v[104:107], v[198:201], v[140:143], v[104:107]
	v_mfma_f32_16x16x32_bf16 v[96:99], v[206:209], v[140:143], v[96:99]
	s_add_u32 s26, s26, 0x80
	s_addc_u32 s27, s27, 0
	v_mfma_f32_16x16x32_bf16 v[88:91], v[198:201], v[148:151], v[88:91]
	v_mfma_f32_16x16x32_bf16 v[80:83], v[206:209], v[148:151], v[80:83]
	v_mfma_f32_16x16x32_bf16 v[72:75], v[198:201], v[156:159], v[72:75]
	v_mfma_f32_16x16x32_bf16 v[64:67], v[206:209], v[156:159], v[64:67]
	s_waitcnt vmcnt(12) lgkmcnt(0)
	s_barrier
	v_mfma_f32_16x16x32_bf16 v[124:127], v[218:221], v[128:131], 0
	v_mfma_f32_16x16x32_bf16 v[116:119], v[226:229], v[128:131], 0
	ds_read_b128 v[160:163], v234 offset:16384
	v_mfma_f32_16x16x32_bf16 v[108:111], v[218:221], v[136:139], 0
	ds_read_b128 v[164:167], v234 offset:17408
	v_mfma_f32_16x16x32_bf16 v[100:103], v[226:229], v[136:139], 0
	ds_read_b128 v[168:171], v234 offset:18432
	s_add_u32 m0, s40, 0x14000
	v_mfma_f32_16x16x32_bf16 v[92:95], v[218:221], v[144:147], 0
	ds_read_b128 v[172:175], v234 offset:19456
	v_mfma_f32_16x16x32_bf16 v[84:87], v[226:229], v[144:147], 0
	ds_read_b128 v[176:179], v234 offset:20480
	global_load_lds_dwordx4 v236, s[38:39]
	v_mfma_f32_16x16x32_bf16 v[76:79], v[218:221], v[152:155], 0
	ds_read_b128 v[180:183], v234 offset:21504
	v_mfma_f32_16x16x32_bf16 v[68:71], v[226:229], v[152:155], 0
	ds_read_b128 v[184:187], v234 offset:22528
	s_add_u32 m0, s40, 0x16000
	v_mfma_f32_16x16x32_bf16 v[124:127], v[222:225], v[132:135], v[124:127]
	ds_read_b128 v[188:191], v234 offset:23552
	v_mfma_f32_16x16x32_bf16 v[116:119], v[230:233], v[132:135], v[116:119]
	global_load_lds_dwordx4 v237, s[38:39]
	v_mfma_f32_16x16x32_bf16 v[108:111], v[222:225], v[140:143], v[108:111]
	v_mfma_f32_16x16x32_bf16 v[100:103], v[230:233], v[140:143], v[100:103]
	s_add_u32 s38, s38, 0x80
	s_addc_u32 s39, s39, 0
	v_mfma_f32_16x16x32_bf16 v[92:95], v[222:225], v[148:151], v[92:95]
	v_mfma_f32_16x16x32_bf16 v[84:87], v[230:233], v[148:151], v[84:87]
	v_mfma_f32_16x16x32_bf16 v[76:79], v[222:225], v[156:159], v[76:79]
	v_mfma_f32_16x16x32_bf16 v[68:71], v[230:233], v[156:159], v[68:71]
	s_waitcnt vmcnt(12) lgkmcnt(0)
	s_barrier
	v_mfma_f32_16x16x32_bf16 v[56:59], v[194:197], v[160:163], 0
	v_mfma_f32_16x16x32_bf16 v[48:51], v[202:205], v[160:163], 0
	ds_read_b128 v[128:131], v234 offset:32768
	v_mfma_f32_16x16x32_bf16 v[40:43], v[194:197], v[168:171], 0
	ds_read_b128 v[132:135], v234 offset:33792
	v_mfma_f32_16x16x32_bf16 v[32:35], v[202:205], v[168:171], 0
	ds_read_b128 v[136:139], v234 offset:34816
	s_add_u32 m0, s40, 0x4000
	v_mfma_f32_16x16x32_bf16 v[24:27], v[194:197], v[176:179], 0
	ds_read_b128 v[140:143], v234 offset:35840
	v_mfma_f32_16x16x32_bf16 v[16:19], v[202:205], v[176:179], 0
	ds_read_b128 v[144:147], v234 offset:36864
	global_load_lds_dwordx4 v236, s[8:9]
	v_mfma_f32_16x16x32_bf16 v[8:11], v[194:197], v[184:187], 0
	ds_read_b128 v[148:151], v234 offset:37888
	v_mfma_f32_16x16x32_bf16 v[0:3], v[202:205], v[184:187], 0
	ds_read_b128 v[152:155], v234 offset:38912
	s_add_u32 m0, s40, 0x6000
	v_mfma_f32_16x16x32_bf16 v[56:59], v[198:201], v[164:167], v[56:59]
	ds_read_b128 v[156:159], v234 offset:39936
	v_mfma_f32_16x16x32_bf16 v[48:51], v[206:209], v[164:167], v[48:51]
	global_load_lds_dwordx4 v237, s[8:9]
	v_mfma_f32_16x16x32_bf16 v[40:43], v[198:201], v[172:175], v[40:43]
	v_mfma_f32_16x16x32_bf16 v[32:35], v[206:209], v[172:175], v[32:35]
	s_add_u32 s8, s8, 0x80
	s_addc_u32 s9, s9, 0
	v_mfma_f32_16x16x32_bf16 v[24:27], v[198:201], v[180:183], v[24:27]
	v_mfma_f32_16x16x32_bf16 v[16:19], v[206:209], v[180:183], v[16:19]
	v_mfma_f32_16x16x32_bf16 v[8:11], v[198:201], v[188:191], v[8:11]
	v_mfma_f32_16x16x32_bf16 v[0:3], v[206:209], v[188:191], v[0:3]
	s_waitcnt vmcnt(12) lgkmcnt(0)
	s_barrier
; #define STAGE(P, BASE, br, kt) do { const u16* _gb = (BASE) + ((size_t)(br) * K + (size_t)(kt) * BK); \
;     __builtin_amdgcn_global_load_lds((const unsigned*)(_gb + goff0), (unsigned*)((char*)(P) + tid * 16), 16, 0, 0); \
;     __builtin_amdgcn_global_load_lds((const unsigned*)(_gb + (size_t)64 * K + goff0), (unsigned*)((char*)(P) + tid * 16 + 8192), 16, 0, 0); } while (0)
; #define LDA(dst, b, h) _Pragma("unroll") for (int m = 0; m < 4; ++m) _Pragma("unroll") for (int k = 0; k < 2; ++k) \
;     dst[m][k] = *reinterpret_cast<const bf16x8*>((char*)SA(b, h) + lds_byte(wr * 64 + m * 16 + fr, k * 32 + fq * 8))
; #define LDB(dst, b, h) _Pragma("unroll") for (int n = 0; n < 2; ++n) _Pragma("unroll") for (int k = 0; k < 2; ++k) \
;     dst[n][k] = *reinterpret_cast<const bf16x8*>((char*)SB(b, h) + lds_byte(wc * 32 + n * 16 + fr, k * 32 + fq * 8))
; #define MMA(ai, bj, At, Bt_) do { __builtin_amdgcn_s_setprio(1); \
;     _Pragma("unroll") for (int m = 0; m < 4; ++m) _Pragma("unroll") for (int n = 0; n < 2; ++n) _Pragma("unroll") for (int k = 0; k < 2; ++k) \
;       acc[ai][bj][m][n] = __builtin_amdgcn_mfma_f32_16x16x32_bf16(Bt_[n][k], At[m][k], acc[ai][bj][m][n], 0, 0, 0); \
;     __builtin_amdgcn_s_setprio(0); } while (0)
; #define WAIT_V(n) asm volatile("s_waitcnt vmcnt(" #n ")" ::: "memory")
; #define WAIT_L(n) asm volatile("s_waitcnt lgkmcnt(" #n ")" ::: "memory")
; #define BAR __builtin_amdgcn_s_barrier()
; #define SCHED __builtin_amdgcn_sched_barrier(0)
; __device__ __forceinline__ void gemm_phase(KP p, char* shmc, const u16* __restrict__ A,
;                                            const u16* __restrict__ Bt, const int N, const int K, const int mode,
;                                            const float* __restrict__ xin, const float resw) {
;     ...
;       LDB(B0, 1, 0); SCHED; LDA(At, 1, 0); STAGE(SA(0, 1), A, brow + HALF, t + 2);
;       WAIT_L(8); BAR; WAIT_L(0); MMA(0, 0, At, B0); BAR; SCHED;
;       LDB(B1, 1, 1); STAGE(SB(1, 0), Bt, bcol, t + 3);
;       BAR; WAIT_L(0); MMA(0, 1, At, B1); BAR;
;       LDA(At, 1, 1); STAGE(SA(1, 0), A, brow, t + 3);
;       BAR; WAIT_L(0); MMA(1, 0, At, B0); BAR; SCHED;
;       STAGE(SB(1, 1), Bt, bcol + HALF, t + 3);
;       WAIT_V(6); BAR; MMA(1, 1, At, B1); BAR;
;     }
	v_mfma_f32_16x16x32_bf16 v[60:63], v[218:221], v[160:163], 0
	v_mfma_f32_16x16x32_bf16 v[52:55], v[226:229], v[160:163], 0
	ds_read_b128 v[194:197], v235 offset:32768
	v_mfma_f32_16x16x32_bf16 v[44:47], v[218:221], v[168:171], 0
	ds_read_b128 v[198:201], v235 offset:33792
	v_mfma_f32_16x16x32_bf16 v[36:39], v[226:229], v[168:171], 0
	ds_read_b128 v[202:205], v235 offset:34816
	s_add_u32 m0, s40, 0x8000
	v_mfma_f32_16x16x32_bf16 v[28:31], v[218:221], v[176:179], 0
	ds_read_b128 v[206:209], v235 offset:35840
	v_mfma_f32_16x16x32_bf16 v[20:23], v[226:229], v[176:179], 0
	global_load_lds_dwordx4 v236, s[36:37]
	v_mfma_f32_16x16x32_bf16 v[12:15], v[218:221], v[184:187], 0
	v_mfma_f32_16x16x32_bf16 v[4:7], v[226:229], v[184:187], 0
	s_add_u32 m0, s40, 0xa000
	v_mfma_f32_16x16x32_bf16 v[60:63], v[222:225], v[164:167], v[60:63]
	v_mfma_f32_16x16x32_bf16 v[52:55], v[230:233], v[164:167], v[52:55]
	global_load_lds_dwordx4 v237, s[36:37]
	v_mfma_f32_16x16x32_bf16 v[44:47], v[222:225], v[172:175], v[44:47]
	v_mfma_f32_16x16x32_bf16 v[36:39], v[230:233], v[172:175], v[36:39]
	s_add_u32 s36, s36, 0x80
	s_addc_u32 s37, s37, 0
	v_mfma_f32_16x16x32_bf16 v[28:31], v[222:225], v[180:183], v[28:31]
	v_mfma_f32_16x16x32_bf16 v[20:23], v[230:233], v[180:183], v[20:23]
	v_mfma_f32_16x16x32_bf16 v[12:15], v[222:225], v[188:191], v[12:15]
	v_mfma_f32_16x16x32_bf16 v[4:7], v[230:233], v[188:191], v[4:7]
	s_waitcnt vmcnt(12) lgkmcnt(0)
	s_barrier
	v_mfma_f32_16x16x32_bf16 v[120:123], v[194:197], v[128:131], v[120:123]
	v_mfma_f32_16x16x32_bf16 v[112:115], v[202:205], v[128:131], v[112:115]
	ds_read_b128 v[218:221], v235 offset:49152
	v_mfma_f32_16x16x32_bf16 v[104:107], v[194:197], v[136:139], v[104:107]
	ds_read_b128 v[222:225], v235 offset:50176
	v_mfma_f32_16x16x32_bf16 v[96:99], v[202:205], v[136:139], v[96:99]
	ds_read_b128 v[226:229], v235 offset:51200
	s_add_u32 m0, s40, 0x18000
	v_mfma_f32_16x16x32_bf16 v[88:91], v[194:197], v[144:147], v[88:91]
	ds_read_b128 v[230:233], v235 offset:52224
	v_mfma_f32_16x16x32_bf16 v[80:83], v[202:205], v[144:147], v[80:83]
	global_load_lds_dwordx4 v236, s[26:27]
	v_mfma_f32_16x16x32_bf16 v[72:75], v[194:197], v[152:155], v[72:75]
	v_mfma_f32_16x16x32_bf16 v[64:67], v[202:205], v[152:155], v[64:67]
	s_add_u32 m0, s40, 0x1a000
	v_mfma_f32_16x16x32_bf16 v[120:123], v[198:201], v[132:135], v[120:123]
	v_mfma_f32_16x16x32_bf16 v[112:115], v[206:209], v[132:135], v[112:115]
	global_load_lds_dwordx4 v237, s[26:27]
	v_mfma_f32_16x16x32_bf16 v[104:107], v[198:201], v[140:143], v[104:107]
	v_mfma_f32_16x16x32_bf16 v[96:99], v[206:209], v[140:143], v[96:99]
	s_add_u32 s26, s26, 0x80
	s_addc_u32 s27, s27, 0
	v_mfma_f32_16x16x32_bf16 v[88:91], v[198:201], v[148:151], v[88:91]
	v_mfma_f32_16x16x32_bf16 v[80:83], v[206:209], v[148:151], v[80:83]
	v_mfma_f32_16x16x32_bf16 v[72:75], v[198:201], v[156:159], v[72:75]
	v_mfma_f32_16x16x32_bf16 v[64:67], v[206:209], v[156:159], v[64:67]
	s_waitcnt vmcnt(12) lgkmcnt(0)
	s_barrier
	v_mfma_f32_16x16x32_bf16 v[124:127], v[218:221], v[128:131], v[124:127]
	v_mfma_f32_16x16x32_bf16 v[116:119], v[226:229], v[128:131], v[116:119]
	ds_read_b128 v[160:163], v234 offset:49152
	v_mfma_f32_16x16x32_bf16 v[108:111], v[218:221], v[136:139], v[108:111]
	ds_read_b128 v[164:167], v234 offset:50176
	v_mfma_f32_16x16x32_bf16 v[100:103], v[226:229], v[136:139], v[100:103]
	ds_read_b128 v[168:171], v234 offset:51200
	s_add_u32 m0, s40, 0x1c000
	v_mfma_f32_16x16x32_bf16 v[92:95], v[218:221], v[144:147], v[92:95]
	ds_read_b128 v[172:175], v234 offset:52224
	v_mfma_f32_16x16x32_bf16 v[84:87], v[226:229], v[144:147], v[84:87]
	ds_read_b128 v[176:179], v234 offset:53248
	global_load_lds_dwordx4 v236, s[38:39]
	v_mfma_f32_16x16x32_bf16 v[76:79], v[218:221], v[152:155], v[76:79]
	ds_read_b128 v[180:183], v234 offset:54272
	v_mfma_f32_16x16x32_bf16 v[68:71], v[226:229], v[152:155], v[68:71]
	ds_read_b128 v[184:187], v234 offset:55296
	s_add_u32 m0, s40, 0x1e000
	v_mfma_f32_16x16x32_bf16 v[124:127], v[222:225], v[132:135], v[124:127]
	ds_read_b128 v[188:191], v234 offset:56320
	v_mfma_f32_16x16x32_bf16 v[116:119], v[230:233], v[132:135], v[116:119]
	global_load_lds_dwordx4 v237, s[38:39]
	v_mfma_f32_16x16x32_bf16 v[108:111], v[222:225], v[140:143], v[108:111]
	v_mfma_f32_16x16x32_bf16 v[100:103], v[230:233], v[140:143], v[100:103]
	s_add_u32 s38, s38, 0x80
	s_addc_u32 s39, s39, 0
	v_mfma_f32_16x16x32_bf16 v[92:95], v[222:225], v[148:151], v[92:95]
	v_mfma_f32_16x16x32_bf16 v[84:87], v[230:233], v[148:151], v[84:87]
	v_mfma_f32_16x16x32_bf16 v[76:79], v[222:225], v[156:159], v[76:79]
	v_mfma_f32_16x16x32_bf16 v[68:71], v[230:233], v[156:159], v[68:71]
	s_waitcnt vmcnt(12) lgkmcnt(0)
	s_barrier
; #define STAGE(P, BASE, br, kt) do { const u16* _gb = (BASE) + ((size_t)(br) * K + (size_t)(kt) * BK); \
;     __builtin_amdgcn_global_load_lds((const unsigned*)(_gb + goff0), (unsigned*)((char*)(P) + tid * 16), 16, 0, 0); \
;     __builtin_amdgcn_global_load_lds((const unsigned*)(_gb + (size_t)64 * K + goff0), (unsigned*)((char*)(P) + tid * 16 + 8192), 16, 0, 0); } while (0)
; #define LDA(dst, b, h) _Pragma("unroll") for (int m = 0; m < 4; ++m) _Pragma("unroll") for (int k = 0; k < 2; ++k) \
;     dst[m][k] = *reinterpret_cast<const bf16x8*>((char*)SA(b, h) + lds_byte(wr * 64 + m * 16 + fr, k * 32 + fq * 8))
; #define LDB(dst, b, h) _Pragma("unroll") for (int n = 0; n < 2; ++n) _Pragma("unroll") for (int k = 0; k < 2; ++k) \
;     dst[n][k] = *reinterpret_cast<const bf16x8*>((char*)SB(b, h) + lds_byte(wc * 32 + n * 16 + fr, k * 32 + fq * 8))
; #define MMA(ai, bj, At, Bt_) do { __builtin_amdgcn_s_setprio(1); \
;     _Pragma("unroll") for (int m = 0; m < 4; ++m) _Pragma("unroll") for (int n = 0; n < 2; ++n) _Pragma("unroll") for (int k = 0; k < 2; ++k) \
;       acc[ai][bj][m][n] = __builtin_amdgcn_mfma_f32_16x16x32_bf16(Bt_[n][k], At[m][k], acc[ai][bj][m][n], 0, 0, 0); \
;     __builtin_amdgcn_s_setprio(0); } while (0)
; #define WAIT_V(n) asm volatile("s_waitcnt vmcnt(" #n ")" ::: "memory")
; #define WAIT_L(n) asm volatile("s_waitcnt lgkmcnt(" #n ")" ::: "memory")
; #define BAR __builtin_amdgcn_s_barrier()
; #define SCHED __builtin_amdgcn_sched_barrier(0)
; __device__ __forceinline__ void gemm_phase(KP p, char* shmc, const u16* __restrict__ A,
;                                            const u16* __restrict__ Bt, const int N, const int K, const int mode,
;                                            const float* __restrict__ xin, const float resw) {
;     ...
;       LDB(B0, 1, 0); SCHED; LDA(At, 1, 0); STAGE(SA(0, 1), A, brow + HALF, t + 2);
;       WAIT_L(8); BAR; WAIT_L(0); MMA(0, 0, At, B0); BAR; SCHED;
;       LDB(B1, 1, 1); STAGE(SB(1, 0), Bt, bcol, t + 3);
;       BAR; WAIT_L(0); MMA(0, 1, At, B1); BAR;
;       LDA(At, 1, 1); STAGE(SA(1, 0), A, brow, t + 3);
;       BAR; WAIT_L(0); MMA(1, 0, At, B0); BAR; SCHED;
;       STAGE(SB(1, 1), Bt, bcol + HALF, t + 3);
;       WAIT_V(6); BAR; MMA(1, 1, At, B1); BAR;
;     }
	v_mfma_f32_16x16x32_bf16 v[56:59], v[194:197], v[160:163], v[56:59]
	v_mfma_f32_16x16x32_bf16 v[48:51], v[202:205], v[160:163], v[48:51]
	ds_read_b128 v[128:131], v234 offset:0
	v_mfma_f32_16x16x32_bf16 v[40:43], v[194:197], v[168:171], v[40:43]
	ds_read_b128 v[132:135], v234 offset:1024
	v_mfma_f32_16x16x32_bf16 v[32:35], v[202:205], v[168:171], v[32:35]
	ds_read_b128 v[136:139], v234 offset:2048
	s_add_u32 m0, s40, 0xc000
	v_mfma_f32_16x16x32_bf16 v[24:27], v[194:197], v[176:179], v[24:27]
	ds_read_b128 v[140:143], v234 offset:3072
	v_mfma_f32_16x16x32_bf16 v[16:19], v[202:205], v[176:179], v[16:19]
	ds_read_b128 v[144:147], v234 offset:4096
	global_load_lds_dwordx4 v236, s[8:9]
	v_mfma_f32_16x16x32_bf16 v[8:11], v[194:197], v[184:187], v[8:11]
	ds_read_b128 v[148:151], v234 offset:5120
	v_mfma_f32_16x16x32_bf16 v[0:3], v[202:205], v[184:187], v[0:3]
	ds_read_b128 v[152:155], v234 offset:6144
	s_add_u32 m0, s40, 0xe000
	v_mfma_f32_16x16x32_bf16 v[56:59], v[198:201], v[164:167], v[56:59]
	ds_read_b128 v[156:159], v234 offset:7168
	v_mfma_f32_16x16x32_bf16 v[48:51], v[206:209], v[164:167], v[48:51]
	global_load_lds_dwordx4 v237, s[8:9]
	v_mfma_f32_16x16x32_bf16 v[40:43], v[198:201], v[172:175], v[40:43]
	v_mfma_f32_16x16x32_bf16 v[32:35], v[206:209], v[172:175], v[32:35]
	s_add_u32 s8, s8, 0x80
	s_addc_u32 s9, s9, 0
	v_mfma_f32_16x16x32_bf16 v[24:27], v[198:201], v[180:183], v[24:27]
	v_mfma_f32_16x16x32_bf16 v[16:19], v[206:209], v[180:183], v[16:19]
	v_mfma_f32_16x16x32_bf16 v[8:11], v[198:201], v[188:191], v[8:11]
	v_mfma_f32_16x16x32_bf16 v[0:3], v[206:209], v[188:191], v[0:3]
	s_waitcnt vmcnt(12) lgkmcnt(0)
	s_barrier
	v_mfma_f32_16x16x32_bf16 v[60:63], v[218:221], v[160:163], v[60:63]
	v_mfma_f32_16x16x32_bf16 v[52:55], v[226:229], v[160:163], v[52:55]
	ds_read_b128 v[194:197], v235 offset:0
	v_mfma_f32_16x16x32_bf16 v[44:47], v[218:221], v[168:171], v[44:47]
	ds_read_b128 v[198:201], v235 offset:1024
	v_mfma_f32_16x16x32_bf16 v[36:39], v[226:229], v[168:171], v[36:39]
	ds_read_b128 v[202:205], v235 offset:2048
	s_add_u32 m0, s40, 0x0
	v_mfma_f32_16x16x32_bf16 v[28:31], v[218:221], v[176:179], v[28:31]
	ds_read_b128 v[206:209], v235 offset:3072
	v_mfma_f32_16x16x32_bf16 v[20:23], v[226:229], v[176:179], v[20:23]
	global_load_lds_dwordx4 v236, s[36:37]
	v_mfma_f32_16x16x32_bf16 v[12:15], v[218:221], v[184:187], v[12:15]
	v_mfma_f32_16x16x32_bf16 v[4:7], v[226:229], v[184:187], v[4:7]
	s_add_u32 m0, s40, 0x2000
	v_mfma_f32_16x16x32_bf16 v[60:63], v[222:225], v[164:167], v[60:63]
	v_mfma_f32_16x16x32_bf16 v[52:55], v[230:233], v[164:167], v[52:55]
	global_load_lds_dwordx4 v237, s[36:37]
	v_mfma_f32_16x16x32_bf16 v[44:47], v[222:225], v[172:175], v[44:47]
	v_mfma_f32_16x16x32_bf16 v[36:39], v[230:233], v[172:175], v[36:39]
	s_add_u32 s36, s36, 0x80
	s_addc_u32 s37, s37, 0
	v_mfma_f32_16x16x32_bf16 v[28:31], v[222:225], v[180:183], v[28:31]
	v_mfma_f32_16x16x32_bf16 v[20:23], v[230:233], v[180:183], v[20:23]
	v_mfma_f32_16x16x32_bf16 v[12:15], v[222:225], v[188:191], v[12:15]
	v_mfma_f32_16x16x32_bf16 v[4:7], v[230:233], v[188:191], v[4:7]
	s_add_i32 s41, s41, -1

; #define STAGE(P, BASE, br, kt) do { const u16* _gb = (BASE) + ((size_t)(br) * K + (size_t)(kt) * BK); \
;     __builtin_amdgcn_global_load_lds((const unsigned*)(_gb + goff0), (unsigned*)((char*)(P) + tid * 16), 16, 0, 0); \
;     __builtin_amdgcn_global_load_lds((const unsigned*)(_gb + (size_t)64 * K + goff0), (unsigned*)((char*)(P) + tid * 16 + 8192), 16, 0, 0); } while (0)
; #define LDA(dst, b, h) _Pragma("unroll") for (int m = 0; m < 4; ++m) _Pragma("unroll") for (int k = 0; k < 2; ++k) \
;     dst[m][k] = *reinterpret_cast<const bf16x8*>((char*)SA(b, h) + lds_byte(wr * 64 + m * 16 + fr, k * 32 + fq * 8))
; #define LDB(dst, b, h) _Pragma("unroll") for (int n = 0; n < 2; ++n) _Pragma("unroll") for (int k = 0; k < 2; ++k) \
;     dst[n][k] = *reinterpret_cast<const bf16x8*>((char*)SB(b, h) + lds_byte(wc * 32 + n * 16 + fr, k * 32 + fq * 8))
; #define WAIT_V(n) asm volatile("s_waitcnt vmcnt(" #n ")" ::: "memory")
; #define WAIT_L(n) asm volatile("s_waitcnt lgkmcnt(" #n ")" ::: "memory")
; #define BAR __builtin_amdgcn_s_barrier()
; #define SCHED __builtin_amdgcn_sched_barrier(0)
; __device__ __forceinline__ void gemm_phase(KP p, char* shmc, const u16* __restrict__ A,
;                                            const u16* __restrict__ Bt, const int N, const int K, const int mode,
;                                            const float* __restrict__ xin, const float resw) {
;     ...
;     f32x4 acc[2][2][4][2];
; #pragma unroll
;     for (int a = 0; a < 2; ++a)
; #pragma unroll
;       for (int b = 0; b < 2; ++b)
; #pragma unroll
;         for (int m = 0; m < 4; ++m)
; #pragma unroll
;           for (int n = 0; n < 2; ++n) acc[a][b][m][n] = f32x4{0.f, 0.f, 0.f, 0.f};
;     bf16x8 At[4][2], B0[2][2], B1[2][2];
;     WAIT_V(0);
;     if (wr == 1) BAR;
;     BAR;
;     for (int t = 0; t < nt - 2; t += 2) {
;       LDB(B0, 0, 0); SCHED; LDA(At, 0, 0); STAGE(SA(1, 1), A, brow + HALF, t + 1);
;       WAIT_L(8); BAR; WAIT_L(0); MMA(0, 0, At, B0); BAR; SCHED;
;       LDB(B1, 0, 1); STAGE(SB(0, 0), Bt, bcol, t + 2);
;       BAR; WAIT_L(0); MMA(0, 1, At, B1); BAR;
;       LDA(At, 0, 1); STAGE(SA(0, 0), A, brow, t + 2);
;       BAR; WAIT_L(0); MMA(1, 0, At, B0); BAR; SCHED;
;       STAGE(SB(0, 1), Bt, bcol + HALF, t + 2);
;       WAIT_V(6); BAR; MMA(1, 1, At, B1); BAR;
.Lmy_entry_sw:
	s_waitcnt vmcnt(12) lgkmcnt(0)
	s_barrier
	v_mfma_f32_16x16x32_bf16 v[120:123], v[128:131], v[194:197], 0
	v_mfma_f32_16x16x32_bf16 v[112:115], v[128:131], v[202:205], 0
	ds_read_b128 v[218:221], v235 offset:16384
	v_mfma_f32_16x16x32_bf16 v[104:107], v[136:139], v[194:197], 0
	ds_read_b128 v[222:225], v235 offset:17408
	v_mfma_f32_16x16x32_bf16 v[96:99], v[136:139], v[202:205], 0
	ds_read_b128 v[226:229], v235 offset:18432
	s_add_u32 m0, s40, 0x10000
	v_mfma_f32_16x16x32_bf16 v[88:91], v[144:147], v[194:197], 0
	ds_read_b128 v[230:233], v235 offset:19456
	v_mfma_f32_16x16x32_bf16 v[80:83], v[144:147], v[202:205], 0
	global_load_lds_dwordx4 v236, s[26:27]
	v_mfma_f32_16x16x32_bf16 v[72:75], v[152:155], v[194:197], 0
	v_mfma_f32_16x16x32_bf16 v[64:67], v[152:155], v[202:205], 0
	s_add_u32 m0, s40, 0x12000
	v_mfma_f32_16x16x32_bf16 v[120:123], v[132:135], v[198:201], v[120:123]
	v_mfma_f32_16x16x32_bf16 v[112:115], v[132:135], v[206:209], v[112:115]
	global_load_lds_dwordx4 v237, s[26:27]
	v_mfma_f32_16x16x32_bf16 v[104:107], v[140:143], v[198:201], v[104:107]
	v_mfma_f32_16x16x32_bf16 v[96:99], v[140:143], v[206:209], v[96:99]
	s_add_u32 s26, s26, 0x80
	s_addc_u32 s27, s27, 0
	v_mfma_f32_16x16x32_bf16 v[88:91], v[148:151], v[198:201], v[88:91]
	v_mfma_f32_16x16x32_bf16 v[80:83], v[148:151], v[206:209], v[80:83]
	v_mfma_f32_16x16x32_bf16 v[72:75], v[156:159], v[198:201], v[72:75]
	v_mfma_f32_16x16x32_bf16 v[64:67], v[156:159], v[206:209], v[64:67]
	s_waitcnt vmcnt(12) lgkmcnt(0)
	s_barrier
	v_mfma_f32_16x16x32_bf16 v[124:127], v[128:131], v[218:221], 0
	v_mfma_f32_16x16x32_bf16 v[116:119], v[128:131], v[226:229], 0
	ds_read_b128 v[160:163], v234 offset:16384
	v_mfma_f32_16x16x32_bf16 v[108:111], v[136:139], v[218:221], 0
	ds_read_b128 v[164:167], v234 offset:17408
	v_mfma_f32_16x16x32_bf16 v[100:103], v[136:139], v[226:229], 0
	ds_read_b128 v[168:171], v234 offset:18432
	s_add_u32 m0, s40, 0x14000
	v_mfma_f32_16x16x32_bf16 v[92:95], v[144:147], v[218:221], 0
	ds_read_b128 v[172:175], v234 offset:19456
	v_mfma_f32_16x16x32_bf16 v[84:87], v[144:147], v[226:229], 0
	ds_read_b128 v[176:179], v234 offset:20480
	global_load_lds_dwordx4 v236, s[38:39]
	v_mfma_f32_16x16x32_bf16 v[76:79], v[152:155], v[218:221], 0
	ds_read_b128 v[180:183], v234 offset:21504
	v_mfma_f32_16x16x32_bf16 v[68:71], v[152:155], v[226:229], 0
	ds_read_b128 v[184:187], v234 offset:22528
	s_add_u32 m0, s40, 0x16000
	v_mfma_f32_16x16x32_bf16 v[124:127], v[132:135], v[222:225], v[124:127]
	ds_read_b128 v[188:191], v234 offset:23552
	v_mfma_f32_16x16x32_bf16 v[116:119], v[132:135], v[230:233], v[116:119]
	global_load_lds_dwordx4 v237, s[38:39]
	v_mfma_f32_16x16x32_bf16 v[108:111], v[140:143], v[222:225], v[108:111]
	v_mfma_f32_16x16x32_bf16 v[100:103], v[140:143], v[230:233], v[100:103]
	s_add_u32 s38, s38, 0x80
	s_addc_u32 s39, s39, 0
	v_mfma_f32_16x16x32_bf16 v[92:95], v[148:151], v[222:225], v[92:95]
	v_mfma_f32_16x16x32_bf16 v[84:87], v[148:151], v[230:233], v[84:87]
	v_mfma_f32_16x16x32_bf16 v[76:79], v[156:159], v[222:225], v[76:79]
	v_mfma_f32_16x16x32_bf16 v[68:71], v[156:159], v[230:233], v[68:71]
	s_waitcnt vmcnt(12) lgkmcnt(0)
	s_barrier
	v_mfma_f32_16x16x32_bf16 v[56:59], v[160:163], v[194:197], 0
	v_mfma_f32_16x16x32_bf16 v[48:51], v[160:163], v[202:205], 0
	ds_read_b128 v[128:131], v234 offset:32768
	v_mfma_f32_16x16x32_bf16 v[40:43], v[168:171], v[194:197], 0
	ds_read_b128 v[132:135], v234 offset:33792
	v_mfma_f32_16x16x32_bf16 v[32:35], v[168:171], v[202:205], 0
	ds_read_b128 v[136:139], v234 offset:34816
	s_add_u32 m0, s40, 0x4000
	v_mfma_f32_16x16x32_bf16 v[24:27], v[176:179], v[194:197], 0
	ds_read_b128 v[140:143], v234 offset:35840
	v_mfma_f32_16x16x32_bf16 v[16:19], v[176:179], v[202:205], 0
	ds_read_b128 v[144:147], v234 offset:36864
	global_load_lds_dwordx4 v236, s[8:9]
	v_mfma_f32_16x16x32_bf16 v[8:11], v[184:187], v[194:197], 0
	ds_read_b128 v[148:151], v234 offset:37888
	v_mfma_f32_16x16x32_bf16 v[0:3], v[184:187], v[202:205], 0
	ds_read_b128 v[152:155], v234 offset:38912
	s_add_u32 m0, s40, 0x6000
	v_mfma_f32_16x16x32_bf16 v[56:59], v[164:167], v[198:201], v[56:59]
	ds_read_b128 v[156:159], v234 offset:39936
	v_mfma_f32_16x16x32_bf16 v[48:51], v[164:167], v[206:209], v[48:51]
	global_load_lds_dwordx4 v237, s[8:9]
	v_mfma_f32_16x16x32_bf16 v[40:43], v[172:175], v[198:201], v[40:43]
	v_mfma_f32_16x16x32_bf16 v[32:35], v[172:175], v[206:209], v[32:35]
	s_add_u32 s8, s8, 0x80
	s_addc_u32 s9, s9, 0
	v_mfma_f32_16x16x32_bf16 v[24:27], v[180:183], v[198:201], v[24:27]
	v_mfma_f32_16x16x32_bf16 v[16:19], v[180:183], v[206:209], v[16:19]
	v_mfma_f32_16x16x32_bf16 v[8:11], v[188:191], v[198:201], v[8:11]
	v_mfma_f32_16x16x32_bf16 v[0:3], v[188:191], v[206:209], v[0:3]
	s_waitcnt vmcnt(12) lgkmcnt(0)
	s_barrier
	v_mfma_f32_16x16x32_bf16 v[60:63], v[160:163], v[218:221], 0
	v_mfma_f32_16x16x32_bf16 v[52:55], v[160:163], v[226:229], 0
	ds_read_b128 v[194:197], v235 offset:32768
	v_mfma_f32_16x16x32_bf16 v[44:47], v[168:171], v[218:221], 0
	ds_read_b128 v[198:201], v235 offset:33792
	v_mfma_f32_16x16x32_bf16 v[36:39], v[168:171], v[226:229], 0
	ds_read_b128 v[202:205], v235 offset:34816
	s_add_u32 m0, s40, 0x8000
	v_mfma_f32_16x16x32_bf16 v[28:31], v[176:179], v[218:221], 0
	ds_read_b128 v[206:209], v235 offset:35840
	v_mfma_f32_16x16x32_bf16 v[20:23], v[176:179], v[226:229], 0
	global_load_lds_dwordx4 v236, s[36:37]
	v_mfma_f32_16x16x32_bf16 v[12:15], v[184:187], v[218:221], 0
	v_mfma_f32_16x16x32_bf16 v[4:7], v[184:187], v[226:229], 0
	s_add_u32 m0, s40, 0xa000
	v_mfma_f32_16x16x32_bf16 v[60:63], v[164:167], v[222:225], v[60:63]
	v_mfma_f32_16x16x32_bf16 v[52:55], v[164:167], v[230:233], v[52:55]
	global_load_lds_dwordx4 v237, s[36:37]
	v_mfma_f32_16x16x32_bf16 v[44:47], v[172:175], v[222:225], v[44:47]
	v_mfma_f32_16x16x32_bf16 v[36:39], v[172:175], v[230:233], v[36:39]
	s_add_u32 s36, s36, 0x80
	s_addc_u32 s37, s37, 0
	v_mfma_f32_16x16x32_bf16 v[28:31], v[180:183], v[222:225], v[28:31]
	v_mfma_f32_16x16x32_bf16 v[20:23], v[180:183], v[230:233], v[20:23]
	v_mfma_f32_16x16x32_bf16 v[12:15], v[188:191], v[222:225], v[12:15]
	v_mfma_f32_16x16x32_bf16 v[4:7], v[188:191], v[230:233], v[4:7]
	s_waitcnt vmcnt(12) lgkmcnt(0)
	s_barrier
; #define STAGE(P, BASE, br, kt) do { const u16* _gb = (BASE) + ((size_t)(br) * K + (size_t)(kt) * BK); \
;     __builtin_amdgcn_global_load_lds((const unsigned*)(_gb + goff0), (unsigned*)((char*)(P) + tid * 16), 16, 0, 0); \
;     __builtin_amdgcn_global_load_lds((const unsigned*)(_gb + (size_t)64 * K + goff0), (unsigned*)((char*)(P) + tid * 16 + 8192), 16, 0, 0); } while (0)
; #define LDA(dst, b, h) _Pragma("unroll") for (int m = 0; m < 4; ++m) _Pragma("unroll") for (int k = 0; k < 2; ++k) \
;     dst[m][k] = *reinterpret_cast<const bf16x8*>((char*)SA(b, h) + lds_byte(wr * 64 + m * 16 + fr, k * 32 + fq * 8))
; #define LDB(dst, b, h) _Pragma("unroll") for (int n = 0; n < 2; ++n) _Pragma("unroll") for (int k = 0; k < 2; ++k) \
;     dst[n][k] = *reinterpret_cast<const bf16x8*>((char*)SB(b, h) + lds_byte(wc * 32 + n * 16 + fr, k * 32 + fq * 8))
; #define MMA(ai, bj, At, Bt_) do { __builtin_amdgcn_s_setprio(1); \
;     _Pragma("unroll") for (int m = 0; m < 4; ++m) _Pragma("unroll") for (int n = 0; n < 2; ++n) _Pragma("unroll") for (int k = 0; k < 2; ++k) \
;       acc[ai][bj][m][n] = __builtin_amdgcn_mfma_f32_16x16x32_bf16(Bt_[n][k], At[m][k], acc[ai][bj][m][n], 0, 0, 0); \
;     __builtin_amdgcn_s_setprio(0); } while (0)
; #define WAIT_V(n) asm volatile("s_waitcnt vmcnt(" #n ")" ::: "memory")
; #define WAIT_L(n) asm volatile("s_waitcnt lgkmcnt(" #n ")" ::: "memory")
; #define BAR __builtin_amdgcn_s_barrier()
; #define SCHED __builtin_amdgcn_sched_barrier(0)
; __device__ __forceinline__ void gemm_phase(KP p, char* shmc, const u16* __restrict__ A,
;                                            const u16* __restrict__ Bt, const int N, const int K, const int mode,
;                                            const float* __restrict__ xin, const float resw) {
;     ...
;       LDB(B0, 1, 0); SCHED; LDA(At, 1, 0); STAGE(SA(0, 1), A, brow + HALF, t + 2);
;       WAIT_L(8); BAR; WAIT_L(0); MMA(0, 0, At, B0); BAR; SCHED;
;       LDB(B1, 1, 1); STAGE(SB(1, 0), Bt, bcol, t + 3);
;       BAR; WAIT_L(0); MMA(0, 1, At, B1); BAR;
;       LDA(At, 1, 1); STAGE(SA(1, 0), A, brow, t + 3);
;       BAR; WAIT_L(0); MMA(1, 0, At, B0); BAR; SCHED;
;       STAGE(SB(1, 1), Bt, bcol + HALF, t + 3);
;       WAIT_V(6); BAR; MMA(1, 1, At, B1); BAR;
;     }
	v_mfma_f32_16x16x32_bf16 v[120:123], v[128:131], v[194:197], v[120:123]
	v_mfma_f32_16x16x32_bf16 v[112:115], v[128:131], v[202:205], v[112:115]
	ds_read_b128 v[218:221], v235 offset:49152
	v_mfma_f32_16x16x32_bf16 v[104:107], v[136:139], v[194:197], v[104:107]
	ds_read_b128 v[222:225], v235 offset:50176
	v_mfma_f32_16x16x32_bf16 v[96:99], v[136:139], v[202:205], v[96:99]
	ds_read_b128 v[226:229], v235 offset:51200
	s_add_u32 m0, s40, 0x18000
	v_mfma_f32_16x16x32_bf16 v[88:91], v[144:147], v[194:197], v[88:91]
	ds_read_b128 v[230:233], v235 offset:52224
	v_mfma_f32_16x16x32_bf16 v[80:83], v[144:147], v[202:205], v[80:83]
	global_load_lds_dwordx4 v236, s[26:27]
	v_mfma_f32_16x16x32_bf16 v[72:75], v[152:155], v[194:197], v[72:75]
	v_mfma_f32_16x16x32_bf16 v[64:67], v[152:155], v[202:205], v[64:67]
	s_add_u32 m0, s40, 0x1a000
	v_mfma_f32_16x16x32_bf16 v[120:123], v[132:135], v[198:201], v[120:123]
	v_mfma_f32_16x16x32_bf16 v[112:115], v[132:135], v[206:209], v[112:115]
	global_load_lds_dwordx4 v237, s[26:27]
	v_mfma_f32_16x16x32_bf16 v[104:107], v[140:143], v[198:201], v[104:107]
	v_mfma_f32_16x16x32_bf16 v[96:99], v[140:143], v[206:209], v[96:99]
	s_add_u32 s26, s26, 0x80
	s_addc_u32 s27, s27, 0
	v_mfma_f32_16x16x32_bf16 v[88:91], v[148:151], v[198:201], v[88:91]
	v_mfma_f32_16x16x32_bf16 v[80:83], v[148:151], v[206:209], v[80:83]
	v_mfma_f32_16x16x32_bf16 v[72:75], v[156:159], v[198:201], v[72:75]
	v_mfma_f32_16x16x32_bf16 v[64:67], v[156:159], v[206:209], v[64:67]
	s_waitcnt vmcnt(12) lgkmcnt(0)
	s_barrier
	v_mfma_f32_16x16x32_bf16 v[124:127], v[128:131], v[218:221], v[124:127]
	v_mfma_f32_16x16x32_bf16 v[116:119], v[128:131], v[226:229], v[116:119]
	ds_read_b128 v[160:163], v234 offset:49152
	v_mfma_f32_16x16x32_bf16 v[108:111], v[136:139], v[218:221], v[108:111]
	ds_read_b128 v[164:167], v234 offset:50176
	v_mfma_f32_16x16x32_bf16 v[100:103], v[136:139], v[226:229], v[100:103]
	ds_read_b128 v[168:171], v234 offset:51200
	s_add_u32 m0, s40, 0x1c000
	v_mfma_f32_16x16x32_bf16 v[92:95], v[144:147], v[218:221], v[92:95]
	ds_read_b128 v[172:175], v234 offset:52224
	v_mfma_f32_16x16x32_bf16 v[84:87], v[144:147], v[226:229], v[84:87]
	ds_read_b128 v[176:179], v234 offset:53248
	global_load_lds_dwordx4 v236, s[38:39]
	v_mfma_f32_16x16x32_bf16 v[76:79], v[152:155], v[218:221], v[76:79]
	ds_read_b128 v[180:183], v234 offset:54272
	v_mfma_f32_16x16x32_bf16 v[68:71], v[152:155], v[226:229], v[68:71]
	ds_read_b128 v[184:187], v234 offset:55296
	s_add_u32 m0, s40, 0x1e000
	v_mfma_f32_16x16x32_bf16 v[124:127], v[132:135], v[222:225], v[124:127]
	ds_read_b128 v[188:191], v234 offset:56320
	v_mfma_f32_16x16x32_bf16 v[116:119], v[132:135], v[230:233], v[116:119]
	global_load_lds_dwordx4 v237, s[38:39]
	v_mfma_f32_16x16x32_bf16 v[108:111], v[140:143], v[222:225], v[108:111]
	v_mfma_f32_16x16x32_bf16 v[100:103], v[140:143], v[230:233], v[100:103]
	s_add_u32 s38, s38, 0x80
	s_addc_u32 s39, s39, 0
	v_mfma_f32_16x16x32_bf16 v[92:95], v[148:151], v[222:225], v[92:95]
	v_mfma_f32_16x16x32_bf16 v[84:87], v[148:151], v[230:233], v[84:87]
	v_mfma_f32_16x16x32_bf16 v[76:79], v[156:159], v[222:225], v[76:79]
	v_mfma_f32_16x16x32_bf16 v[68:71], v[156:159], v[230:233], v[68:71]
	s_waitcnt vmcnt(12) lgkmcnt(0)
	s_barrier
	v_mfma_f32_16x16x32_bf16 v[56:59], v[160:163], v[194:197], v[56:59]
	v_mfma_f32_16x16x32_bf16 v[48:51], v[160:163], v[202:205], v[48:51]
	ds_read_b128 v[128:131], v234 offset:0
	v_mfma_f32_16x16x32_bf16 v[40:43], v[168:171], v[194:197], v[40:43]
	ds_read_b128 v[132:135], v234 offset:1024
	v_mfma_f32_16x16x32_bf16 v[32:35], v[168:171], v[202:205], v[32:35]
	ds_read_b128 v[136:139], v234 offset:2048
	s_add_u32 m0, s40, 0xc000
	v_mfma_f32_16x16x32_bf16 v[24:27], v[176:179], v[194:197], v[24:27]
	ds_read_b128 v[140:143], v234 offset:3072
	v_mfma_f32_16x16x32_bf16 v[16:19], v[176:179], v[202:205], v[16:19]
	ds_read_b128 v[144:147], v234 offset:4096
	global_load_lds_dwordx4 v236, s[8:9]
	v_mfma_f32_16x16x32_bf16 v[8:11], v[184:187], v[194:197], v[8:11]
	ds_read_b128 v[148:151], v234 offset:5120
	v_mfma_f32_16x16x32_bf16 v[0:3], v[184:187], v[202:205], v[0:3]
	ds_read_b128 v[152:155], v234 offset:6144
	s_add_u32 m0, s40, 0xe000
	v_mfma_f32_16x16x32_bf16 v[56:59], v[164:167], v[198:201], v[56:59]
	ds_read_b128 v[156:159], v234 offset:7168
	v_mfma_f32_16x16x32_bf16 v[48:51], v[164:167], v[206:209], v[48:51]
	global_load_lds_dwordx4 v237, s[8:9]
	v_mfma_f32_16x16x32_bf16 v[40:43], v[172:175], v[198:201], v[40:43]
	v_mfma_f32_16x16x32_bf16 v[32:35], v[172:175], v[206:209], v[32:35]
	s_add_u32 s8, s8, 0x80
	s_addc_u32 s9, s9, 0
	v_mfma_f32_16x16x32_bf16 v[24:27], v[180:183], v[198:201], v[24:27]
	v_mfma_f32_16x16x32_bf16 v[16:19], v[180:183], v[206:209], v[16:19]
	v_mfma_f32_16x16x32_bf16 v[8:11], v[188:191], v[198:201], v[8:11]
	v_mfma_f32_16x16x32_bf16 v[0:3], v[188:191], v[206:209], v[0:3]
	s_waitcnt vmcnt(12) lgkmcnt(0)
	s_barrier
	v_mfma_f32_16x16x32_bf16 v[60:63], v[160:163], v[218:221], v[60:63]
	v_mfma_f32_16x16x32_bf16 v[52:55], v[160:163], v[226:229], v[52:55]
	ds_read_b128 v[194:197], v235 offset:0
	v_mfma_f32_16x16x32_bf16 v[44:47], v[168:171], v[218:221], v[44:47]
	ds_read_b128 v[198:201], v235 offset:1024
	v_mfma_f32_16x16x32_bf16 v[36:39], v[168:171], v[226:229], v[36:39]
	ds_read_b128 v[202:205], v235 offset:2048
	s_add_u32 m0, s40, 0x0
	v_mfma_f32_16x16x32_bf16 v[28:31], v[176:179], v[218:221], v[28:31]
	ds_read_b128 v[206:209], v235 offset:3072
	v_mfma_f32_16x16x32_bf16 v[20:23], v[176:179], v[226:229], v[20:23]
	global_load_lds_dwordx4 v236, s[36:37]
	v_mfma_f32_16x16x32_bf16 v[12:15], v[184:187], v[218:221], v[12:15]
	v_mfma_f32_16x16x32_bf16 v[4:7], v[184:187], v[226:229], v[4:7]
	s_add_u32 m0, s40, 0x2000
	v_mfma_f32_16x16x32_bf16 v[60:63], v[164:167], v[222:225], v[60:63]
	v_mfma_f32_16x16x32_bf16 v[52:55], v[164:167], v[230:233], v[52:55]
	global_load_lds_dwordx4 v237, s[36:37]
	v_mfma_f32_16x16x32_bf16 v[44:47], v[172:175], v[222:225], v[44:47]
	v_mfma_f32_16x16x32_bf16 v[36:39], v[172:175], v[230:233], v[36:39]
	s_add_u32 s36, s36, 0x80
	s_addc_u32 s37, s37, 0
	v_mfma_f32_16x16x32_bf16 v[28:31], v[180:183], v[222:225], v[28:31]
	v_mfma_f32_16x16x32_bf16 v[20:23], v[180:183], v[230:233], v[20:23]
	v_mfma_f32_16x16x32_bf16 v[12:15], v[188:191], v[222:225], v[12:15]
	v_mfma_f32_16x16x32_bf16 v[4:7], v[188:191], v[230:233], v[4:7]
	s_add_i32 s41, s41, -1
